# sample-stream scans moved to blocks 192-255 (free first: one prep item, then scan), second-round context tasks on blocks 0-63; chunk-MLP staging loads de-serialized
# speedup vs baseline: 1.0183x; 1.0012x over previous
.LBB0_473:
	s_or_b64 exec, exec, s[10:11]
	s_waitcnt vmcnt(0)
	s_barrier
	v_readfirstlane_b32 s14, v243
	s_and_b32 s14, s14, 0xffffffe0
	s_lshr_b32 s15, s14, 8
	s_sub_u32 s20, s14, 0x1000
	s_lshr_b32 s20, s20, 10
	s_add_u32 s20, s20, 16
	s_cmp_lt_u32 s14, 0x1000
	s_cselect_b32 s15, s15, s20
	s_lshl_b32 s14, s80, 5
	s_add_u32 s15, s15, s14
	s_add_u32 s15, s15, 8
	s_lshl_b32 s15, s15, 2
	v_readlane_b32 s20, v253, 2
	v_readlane_b32 s21, v253, 3
	s_nop 0
	s_add_u32 s20, s20, s15
	s_addc_u32 s21, s21, 0
	v_cmp_eq_u32_e32 vcc, 0, v0
	s_and_saveexec_b64 s[10:11], vcc
	v_mov_b32_e32 v2, 1
	global_atomic_add v131, v2, s[20:21]
	s_or_b64 exec, exec, s[10:11]
	s_cmpk_ge_u32 s2, 0xc0
	s_cbranch_scc1 .Ldf_b0skip

.LBB0_568:
	s_or_b64 exec, exec, s[0:1]
	v_mov_b32_e32 v1, v0
	s_waitcnt lgkmcnt(0)
	s_barrier
	s_movk_i32 s0, 0x3000
	v_ashrrev_i32_e32 v89, 6, v1
	v_readlane_b32 s4, v253, 43
	v_mul_lo_u32 v2, v89, s0
	v_readlane_b32 s5, v253, 44
	v_add_u32_e32 v110, 0xf0, v2
	v_readfirstlane_b32 s0, v89
	v_readlane_b32 s70, v253, 52
	s_mov_b32 s71, s2
	s_add_u32 s71, s2, 64
	s_and_b32 s71, s71, 255
	s_lshr_b32 s70, s70, 1
	s_mov_b32 s25, 0

.Lsc_next:
	s_add_u32 s25, s25, 1
	s_mul_i32 s1, s25, s70
	s_sub_u32 s4, s70, 1
	s_sub_u32 s4, s4, s2
	s_bitcmp1_b32 s25, 0
	s_cselect_b32 s4, s4, s2
	s_mov_b32 s4, s2
	s_add_u32 s71, s1, s4
	s_branch .Lsc_task_loop
